# conv_item rewritten by hand: per thread 4 channels x 16 tokens, each 3x3 row's 10 u rows + 3 tap weights loaded once (13 loads in flight, two row buffers), f32 fma taps in original order
# speedup vs baseline: 1.0275x; 1.0233x over previous
.LBB0_379:
	s_andn2_b64 vcc, exec, s[0:1]
	s_cbranch_vccnz .LBB0_313
	v_mov_b32_e32 v12, v172
	s_movk_i32 s0, 0xc00
	s_nop 0
	v_cmp_gt_i32_e32 vcc, s0, v12
	s_and_saveexec_b64 s[12:13], vcc
	s_cbranch_execz .LBB0_312
	s_lshl_b32 s29, s16, 4
	v_readfirstlane_b32 s14, v172
	v_and_b32_e32 v220, 0x7f, v172
	v_lshlrev_b32_e32 v220, 4, v220
	s_nop 1
	s_lshr_b32 s14, s14, 6
	s_cmp_gt_u32 s14, 2
	s_cbranch_scc1 .LBB0_312
	s_cmp_lt_u32 s14, 2
	s_cselect_b32 s2, s7, s23
	s_cselect_b32 s3, s22, s24
	s_cselect_b32 s54, s11, s26
	s_cselect_b32 s55, s25, s27
	s_movk_i32 s4, 0x2c60
	s_cselect_b32 s32, 0x1000, s4
	s_movk_i32 s4, 0x400
	s_cselect_b32 s39, 0x800, s4
	s_cselect_b32 s48, 1, 0
	s_mov_b32 s4, 0x16ca4000
	s_cselect_b32 s49, 0x154a4000, s4
	global_load_dwordx4 v[222:225], v220, s[54:55]
	s_mul_i32 s4, s29, s39
	s_add_u32 s4, s4, s49
	s_add_u32 s72, s82, s4
	s_addc_u32 s73, s83, 0
	s_mul_i32 s4, s29, 0x3a00
	s_add_u32 s4, s4, s32
	s_add_u32 s74, s94, s4
	s_addc_u32 s75, s95, 0
	s_cmp_lt_u32 s29, 0x1000
	s_cbranch_scc1 .Lcv_ctx
	s_bfe_u32 s4, s29, 0x60006
	s_mov_b32 s15, 2
	s_cmp_lg_u32 s4, 0
	s_cselect_b32 s5, 1, 0
	s_or_b32 s15, s15, s5
	s_cmp_lg_u32 s4, 63
	s_cselect_b32 s5, 4, 0
	s_or_b32 s15, s15, s5
	s_mov_b32 s49, 63
	s_branch .Lcv_flags
.Lcv_ctx:
	s_mov_b32 s15, 2
	s_movk_i32 s49, 0xff
.Lcv_flags:
	s_and_b32 s4, s29, s49
	s_cmp_eq_u32 s4, 0
	s_cselect_b32 s5, 8, 0
	s_or_b32 s15, s15, s5
	s_add_u32 s4, s29, 16
	s_and_b32 s4, s4, s49
	s_cmp_eq_u32 s4, 0
	s_cselect_b32 s5, 16, 0
	s_or_b32 s15, s15, s5
	s_mov_b32 s16, 0
.Lcv_half:
	s_lshr_b32 s4, s15, 3
	s_cmp_eq_u32 s16, 0
	s_cselect_b32 s5, 1, 2
	s_mov_b32 s98, 0x19600
	s_cselect_b32 s98, 0xffffc600, s98
	s_cselect_b32 s99, -1, 0
	s_and_b32 s17, s4, s5
	s_add_u32 s76, s74, s98
	s_addc_u32 s77, s75, s99
	s_bitcmp1_b32 s15, 0
	s_cbranch_scc0 .Lcv_nor0
	s_sub_u32 s0, s76, 0xe8000
	s_subb_u32 s1, s77, 0
	s_bitcmp1_b32 s17, 0
	s_cselect_b32 s4, 0x3a00, 0
	s_add_u32 s98, s0, s4
	s_addc_u32 s99, s1, 0
	global_load_dwordx4 v[88:91], v220, s[98:99]
	s_add_u32 s0, s0, 0x3a00
	s_addc_u32 s1, s1, 0
	global_load_dwordx4 v[92:95], v220, s[0:1]
	s_add_u32 s0, s0, 0x3a00
	s_addc_u32 s1, s1, 0
	global_load_dwordx4 v[96:99], v220, s[0:1]
	s_add_u32 s0, s0, 0x3a00
	s_addc_u32 s1, s1, 0
	global_load_dwordx4 v[100:103], v220, s[0:1]
	s_add_u32 s0, s0, 0x3a00
	s_addc_u32 s1, s1, 0
	global_load_dwordx4 v[104:107], v220, s[0:1]
	s_add_u32 s0, s0, 0x3a00
	s_addc_u32 s1, s1, 0
	global_load_dwordx4 v[108:111], v220, s[0:1]
	s_add_u32 s0, s0, 0x3a00
	s_addc_u32 s1, s1, 0
	global_load_dwordx4 v[112:115], v220, s[0:1]
	s_add_u32 s0, s0, 0x3a00
	s_addc_u32 s1, s1, 0
	global_load_dwordx4 v[116:119], v220, s[0:1]
	s_add_u32 s0, s0, 0x3a00
	s_addc_u32 s1, s1, 0
	global_load_dwordx4 v[120:123], v220, s[0:1]
	s_bitcmp1_b32 s17, 1
	s_cselect_b32 s4, 0, 0x3a00
	s_add_u32 s0, s0, s4
	s_addc_u32 s1, s1, 0
	global_load_dwordx4 v[124:127], v220, s[0:1]
	s_mul_i32 s4, s39, 0
	s_add_u32 s98, s2, s4
	s_addc_u32 s99, s3, 0
	global_load_dwordx4 v[208:211], v220, s[98:99]
	s_add_u32 s98, s98, s39
	s_addc_u32 s99, s99, 0
	global_load_dwordx4 v[212:215], v220, s[98:99]
	s_add_u32 s98, s98, s39
	s_addc_u32 s99, s99, 0
	global_load_dwordx4 v[216:219], v220, s[98:99]
.Lcv_nor0:
	s_mov_b64 s[0:1], s[76:77]
	s_bitcmp1_b32 s17, 0
	s_cselect_b32 s4, 0x3a00, 0
	s_add_u32 s98, s0, s4
	s_addc_u32 s99, s1, 0
	global_load_dwordx4 v[128:131], v220, s[98:99]
	s_add_u32 s0, s0, 0x3a00
	s_addc_u32 s1, s1, 0
	global_load_dwordx4 v[132:135], v220, s[0:1]
	s_add_u32 s0, s0, 0x3a00
	s_addc_u32 s1, s1, 0
	global_load_dwordx4 v[136:139], v220, s[0:1]
	s_add_u32 s0, s0, 0x3a00
	s_addc_u32 s1, s1, 0
	global_load_dwordx4 v[140:143], v220, s[0:1]
	s_add_u32 s0, s0, 0x3a00
	s_addc_u32 s1, s1, 0
	global_load_dwordx4 v[152:155], v220, s[0:1]
	s_add_u32 s0, s0, 0x3a00
	s_addc_u32 s1, s1, 0
	global_load_dwordx4 v[156:159], v220, s[0:1]
	s_add_u32 s0, s0, 0x3a00
	s_addc_u32 s1, s1, 0
	global_load_dwordx4 v[160:163], v220, s[0:1]
	s_add_u32 s0, s0, 0x3a00
	s_addc_u32 s1, s1, 0
	global_load_dwordx4 v[164:167], v220, s[0:1]
	s_add_u32 s0, s0, 0x3a00
	s_addc_u32 s1, s1, 0
	global_load_dwordx4 v[168:171], v220, s[0:1]
	s_bitcmp1_b32 s17, 1
	s_cselect_b32 s4, 0, 0x3a00
	s_add_u32 s0, s0, s4
	s_addc_u32 s1, s1, 0
	global_load_dwordx4 v[204:207], v220, s[0:1]
	s_mul_i32 s4, s39, 3
	s_add_u32 s98, s2, s4
	s_addc_u32 s99, s3, 0
	global_load_dwordx4 v[234:237], v220, s[98:99]
	s_add_u32 s98, s98, s39
	s_addc_u32 s99, s99, 0
	global_load_dwordx4 v[238:241], v220, s[98:99]
	s_add_u32 s98, s98, s39
	s_addc_u32 s99, s99, 0
	global_load_dwordx4 v[242:245], v220, s[98:99]
	s_waitcnt vmcnt(13)
	v_mov_b64_e32 v[0:1], v[222:223]
	v_mov_b64_e32 v[2:3], v[224:225]
	v_mov_b64_e32 v[4:5], v[222:223]
	v_mov_b64_e32 v[6:7], v[224:225]
	v_mov_b64_e32 v[8:9], v[222:223]
	v_mov_b64_e32 v[10:11], v[224:225]
	v_mov_b64_e32 v[12:13], v[222:223]
	v_mov_b64_e32 v[14:15], v[224:225]
	v_mov_b64_e32 v[16:17], v[222:223]
	v_mov_b64_e32 v[18:19], v[224:225]
	v_mov_b64_e32 v[20:21], v[222:223]
	v_mov_b64_e32 v[22:23], v[224:225]
	v_mov_b64_e32 v[24:25], v[222:223]
	v_mov_b64_e32 v[26:27], v[224:225]
	v_mov_b64_e32 v[28:29], v[222:223]
	v_mov_b64_e32 v[30:31], v[224:225]
	s_bitcmp1_b32 s15, 0
	s_cbranch_scc0 .Lcv_noc0
	s_bitcmp1_b32 s17, 0
	s_cbranch_scc0 .Lcv_z0_r0
	v_mov_b64_e32 v[88:89], 0
	v_mov_b64_e32 v[90:91], 0
.Lcv_z0_r0:
	s_bitcmp1_b32 s17, 1
	s_cbranch_scc0 .Lcv_z9_r0
	v_mov_b64_e32 v[124:125], 0
	v_mov_b64_e32 v[126:127], 0
.Lcv_z9_r0:
	v_pk_fma_f32 v[0:1], v[88:89], v[208:209], v[0:1]
	v_pk_fma_f32 v[2:3], v[90:91], v[210:211], v[2:3]
	v_pk_fma_f32 v[4:5], v[92:93], v[208:209], v[4:5]
	v_pk_fma_f32 v[6:7], v[94:95], v[210:211], v[6:7]
	v_pk_fma_f32 v[8:9], v[96:97], v[208:209], v[8:9]
	v_pk_fma_f32 v[10:11], v[98:99], v[210:211], v[10:11]
	v_pk_fma_f32 v[12:13], v[100:101], v[208:209], v[12:13]
	v_pk_fma_f32 v[14:15], v[102:103], v[210:211], v[14:15]
	v_pk_fma_f32 v[16:17], v[104:105], v[208:209], v[16:17]
	v_pk_fma_f32 v[18:19], v[106:107], v[210:211], v[18:19]
	v_pk_fma_f32 v[20:21], v[108:109], v[208:209], v[20:21]
	v_pk_fma_f32 v[22:23], v[110:111], v[210:211], v[22:23]
	v_pk_fma_f32 v[24:25], v[112:113], v[208:209], v[24:25]
	v_pk_fma_f32 v[26:27], v[114:115], v[210:211], v[26:27]
	v_pk_fma_f32 v[28:29], v[116:117], v[208:209], v[28:29]
	v_pk_fma_f32 v[30:31], v[118:119], v[210:211], v[30:31]
	v_pk_fma_f32 v[0:1], v[92:93], v[212:213], v[0:1]
	v_pk_fma_f32 v[2:3], v[94:95], v[214:215], v[2:3]
	v_pk_fma_f32 v[4:5], v[96:97], v[212:213], v[4:5]
	v_pk_fma_f32 v[6:7], v[98:99], v[214:215], v[6:7]
	v_pk_fma_f32 v[8:9], v[100:101], v[212:213], v[8:9]
	v_pk_fma_f32 v[10:11], v[102:103], v[214:215], v[10:11]
	v_pk_fma_f32 v[12:13], v[104:105], v[212:213], v[12:13]
	v_pk_fma_f32 v[14:15], v[106:107], v[214:215], v[14:15]
	v_pk_fma_f32 v[16:17], v[108:109], v[212:213], v[16:17]
	v_pk_fma_f32 v[18:19], v[110:111], v[214:215], v[18:19]
	v_pk_fma_f32 v[20:21], v[112:113], v[212:213], v[20:21]
	v_pk_fma_f32 v[22:23], v[114:115], v[214:215], v[22:23]
	v_pk_fma_f32 v[24:25], v[116:117], v[212:213], v[24:25]
	v_pk_fma_f32 v[26:27], v[118:119], v[214:215], v[26:27]
	v_pk_fma_f32 v[28:29], v[120:121], v[212:213], v[28:29]
	v_pk_fma_f32 v[30:31], v[122:123], v[214:215], v[30:31]
	v_pk_fma_f32 v[0:1], v[96:97], v[216:217], v[0:1]
	v_pk_fma_f32 v[2:3], v[98:99], v[218:219], v[2:3]
	v_pk_fma_f32 v[4:5], v[100:101], v[216:217], v[4:5]
	v_pk_fma_f32 v[6:7], v[102:103], v[218:219], v[6:7]
	v_pk_fma_f32 v[8:9], v[104:105], v[216:217], v[8:9]
	v_pk_fma_f32 v[10:11], v[106:107], v[218:219], v[10:11]
	v_pk_fma_f32 v[12:13], v[108:109], v[216:217], v[12:13]
	v_pk_fma_f32 v[14:15], v[110:111], v[218:219], v[14:15]
	v_pk_fma_f32 v[16:17], v[112:113], v[216:217], v[16:17]
	v_pk_fma_f32 v[18:19], v[114:115], v[218:219], v[18:19]
	v_pk_fma_f32 v[20:21], v[116:117], v[216:217], v[20:21]
	v_pk_fma_f32 v[22:23], v[118:119], v[218:219], v[22:23]
	v_pk_fma_f32 v[24:25], v[120:121], v[216:217], v[24:25]
	v_pk_fma_f32 v[26:27], v[122:123], v[218:219], v[26:27]
	v_pk_fma_f32 v[28:29], v[124:125], v[216:217], v[28:29]
	v_pk_fma_f32 v[30:31], v[126:127], v[218:219], v[30:31]
.Lcv_noc0:
	s_bitcmp1_b32 s15, 2
	s_cbranch_scc0 .Lcv_nor2
	s_add_u32 s0, s76, 0xe8000
	s_addc_u32 s1, s77, 0
	s_bitcmp1_b32 s17, 0
	s_cselect_b32 s4, 0x3a00, 0
	s_add_u32 s98, s0, s4
	s_addc_u32 s99, s1, 0
	global_load_dwordx4 v[88:91], v220, s[98:99]
	s_add_u32 s0, s0, 0x3a00
	s_addc_u32 s1, s1, 0
	global_load_dwordx4 v[92:95], v220, s[0:1]
	s_add_u32 s0, s0, 0x3a00
	s_addc_u32 s1, s1, 0
	global_load_dwordx4 v[96:99], v220, s[0:1]
	s_add_u32 s0, s0, 0x3a00
	s_addc_u32 s1, s1, 0
	global_load_dwordx4 v[100:103], v220, s[0:1]
	s_add_u32 s0, s0, 0x3a00
	s_addc_u32 s1, s1, 0
	global_load_dwordx4 v[104:107], v220, s[0:1]
	s_add_u32 s0, s0, 0x3a00
	s_addc_u32 s1, s1, 0
	global_load_dwordx4 v[108:111], v220, s[0:1]
	s_add_u32 s0, s0, 0x3a00
	s_addc_u32 s1, s1, 0
	global_load_dwordx4 v[112:115], v220, s[0:1]
	s_add_u32 s0, s0, 0x3a00
	s_addc_u32 s1, s1, 0
	global_load_dwordx4 v[116:119], v220, s[0:1]
	s_add_u32 s0, s0, 0x3a00
	s_addc_u32 s1, s1, 0
	global_load_dwordx4 v[120:123], v220, s[0:1]
	s_bitcmp1_b32 s17, 1
	s_cselect_b32 s4, 0, 0x3a00
	s_add_u32 s0, s0, s4
	s_addc_u32 s1, s1, 0
	global_load_dwordx4 v[124:127], v220, s[0:1]
	s_mul_i32 s4, s39, 6
	s_add_u32 s98, s2, s4
	s_addc_u32 s99, s3, 0
	global_load_dwordx4 v[208:211], v220, s[98:99]
	s_add_u32 s98, s98, s39
	s_addc_u32 s99, s99, 0
	global_load_dwordx4 v[212:215], v220, s[98:99]
	s_add_u32 s98, s98, s39
	s_addc_u32 s99, s99, 0
	global_load_dwordx4 v[216:219], v220, s[98:99]
	s_waitcnt vmcnt(13)
	s_branch .Lcv_c1

.Lcv_c1:
	s_bitcmp1_b32 s17, 0
	s_cbranch_scc0 .Lcv_z0_r1
	v_mov_b64_e32 v[128:129], 0
	v_mov_b64_e32 v[130:131], 0
.Lcv_z0_r1:
	s_bitcmp1_b32 s17, 1
	s_cbranch_scc0 .Lcv_z9_r1
	v_mov_b64_e32 v[204:205], 0
	v_mov_b64_e32 v[206:207], 0
.Lcv_z9_r1:
	v_pk_fma_f32 v[0:1], v[128:129], v[234:235], v[0:1]
	v_pk_fma_f32 v[2:3], v[130:131], v[236:237], v[2:3]
	v_pk_fma_f32 v[4:5], v[132:133], v[234:235], v[4:5]
	v_pk_fma_f32 v[6:7], v[134:135], v[236:237], v[6:7]
	v_pk_fma_f32 v[8:9], v[136:137], v[234:235], v[8:9]
	v_pk_fma_f32 v[10:11], v[138:139], v[236:237], v[10:11]
	v_pk_fma_f32 v[12:13], v[140:141], v[234:235], v[12:13]
	v_pk_fma_f32 v[14:15], v[142:143], v[236:237], v[14:15]
	v_pk_fma_f32 v[16:17], v[152:153], v[234:235], v[16:17]
	v_pk_fma_f32 v[18:19], v[154:155], v[236:237], v[18:19]
	v_pk_fma_f32 v[20:21], v[156:157], v[234:235], v[20:21]
	v_pk_fma_f32 v[22:23], v[158:159], v[236:237], v[22:23]
	v_pk_fma_f32 v[24:25], v[160:161], v[234:235], v[24:25]
	v_pk_fma_f32 v[26:27], v[162:163], v[236:237], v[26:27]
	v_pk_fma_f32 v[28:29], v[164:165], v[234:235], v[28:29]
	v_pk_fma_f32 v[30:31], v[166:167], v[236:237], v[30:31]
	v_pk_fma_f32 v[0:1], v[132:133], v[238:239], v[0:1]
	v_pk_fma_f32 v[2:3], v[134:135], v[240:241], v[2:3]
	v_pk_fma_f32 v[4:5], v[136:137], v[238:239], v[4:5]
	v_pk_fma_f32 v[6:7], v[138:139], v[240:241], v[6:7]
	v_pk_fma_f32 v[8:9], v[140:141], v[238:239], v[8:9]
	v_pk_fma_f32 v[10:11], v[142:143], v[240:241], v[10:11]
	v_pk_fma_f32 v[12:13], v[152:153], v[238:239], v[12:13]
	v_pk_fma_f32 v[14:15], v[154:155], v[240:241], v[14:15]
	v_pk_fma_f32 v[16:17], v[156:157], v[238:239], v[16:17]
	v_pk_fma_f32 v[18:19], v[158:159], v[240:241], v[18:19]
	v_pk_fma_f32 v[20:21], v[160:161], v[238:239], v[20:21]
	v_pk_fma_f32 v[22:23], v[162:163], v[240:241], v[22:23]
	v_pk_fma_f32 v[24:25], v[164:165], v[238:239], v[24:25]
	v_pk_fma_f32 v[26:27], v[166:167], v[240:241], v[26:27]
	v_pk_fma_f32 v[28:29], v[168:169], v[238:239], v[28:29]
	v_pk_fma_f32 v[30:31], v[170:171], v[240:241], v[30:31]
	v_pk_fma_f32 v[0:1], v[136:137], v[242:243], v[0:1]
	v_pk_fma_f32 v[2:3], v[138:139], v[244:245], v[2:3]
	v_pk_fma_f32 v[4:5], v[140:141], v[242:243], v[4:5]
	v_pk_fma_f32 v[6:7], v[142:143], v[244:245], v[6:7]
	v_pk_fma_f32 v[8:9], v[152:153], v[242:243], v[8:9]
	v_pk_fma_f32 v[10:11], v[154:155], v[244:245], v[10:11]
	v_pk_fma_f32 v[12:13], v[156:157], v[242:243], v[12:13]
	v_pk_fma_f32 v[14:15], v[158:159], v[244:245], v[14:15]
	v_pk_fma_f32 v[16:17], v[160:161], v[242:243], v[16:17]
	v_pk_fma_f32 v[18:19], v[162:163], v[244:245], v[18:19]
	v_pk_fma_f32 v[20:21], v[164:165], v[242:243], v[20:21]
	v_pk_fma_f32 v[22:23], v[166:167], v[244:245], v[22:23]
	v_pk_fma_f32 v[24:25], v[168:169], v[242:243], v[24:25]
	v_pk_fma_f32 v[26:27], v[170:171], v[244:245], v[26:27]
	v_pk_fma_f32 v[28:29], v[204:205], v[242:243], v[28:29]
	v_pk_fma_f32 v[30:31], v[206:207], v[244:245], v[30:31]
	s_bitcmp1_b32 s15, 2
	s_cbranch_scc0 .Lcv_noc2
	s_waitcnt vmcnt(0)
	s_bitcmp1_b32 s17, 0
	s_cbranch_scc0 .Lcv_z0_r2
	v_mov_b64_e32 v[88:89], 0
	v_mov_b64_e32 v[90:91], 0

.Lcv_noc2:
	s_cmp_eq_u32 s48, 0
	s_cbranch_scc1 .Lcv_nosilu
	v_mul_f32_e32 v88, 0xbfb8aa3b, v0
	v_mul_f32_e32 v89, 0xbfb8aa3b, v1
	v_exp_f32_e32 v88, v88
	v_exp_f32_e32 v89, v89
	s_nop 0
	v_pk_add_f32 v[88:89], v[88:89], 1.0 op_sel_hi:[1,0]
	s_nop 0
	v_div_scale_f32 v90, s[4:5], v89, v89, 1.0
	v_rcp_f32_e32 v91, v90
	s_nop 0
	v_fma_f32 v92, -v90, v91, 1.0
	v_fmac_f32_e32 v91, v92, v91
	v_div_scale_f32 v92, vcc, 1.0, v89, 1.0
	v_mul_f32_e32 v93, v92, v91
	v_fma_f32 v94, -v90, v93, v92
	v_fmac_f32_e32 v93, v94, v91
	v_fma_f32 v90, -v90, v93, v92
	v_div_fmas_f32 v90, v90, v91, v93
	v_div_fixup_f32 v89, v90, v89, 1.0
	v_div_scale_f32 v90, s[4:5], v88, v88, 1.0
	v_rcp_f32_e32 v91, v90
	s_nop 0
	v_fma_f32 v92, -v90, v91, 1.0
	v_fmac_f32_e32 v91, v92, v91
	v_div_scale_f32 v92, vcc, 1.0, v88, 1.0
	v_mul_f32_e32 v93, v92, v91
	v_fma_f32 v94, -v90, v93, v92
	v_fmac_f32_e32 v93, v94, v91
	v_fma_f32 v90, -v90, v93, v92
	v_div_fmas_f32 v90, v90, v91, v93
	v_div_fixup_f32 v88, v90, v88, 1.0
	v_pk_mul_f32 v[0:1], v[0:1], v[88:89]
	v_mul_f32_e32 v88, 0xbfb8aa3b, v2
	v_mul_f32_e32 v89, 0xbfb8aa3b, v3
	v_exp_f32_e32 v88, v88
	v_exp_f32_e32 v89, v89
	s_nop 0
	v_pk_add_f32 v[88:89], v[88:89], 1.0 op_sel_hi:[1,0]
	s_nop 0
	v_div_scale_f32 v90, s[4:5], v89, v89, 1.0
	v_rcp_f32_e32 v91, v90
	s_nop 0
	v_fma_f32 v92, -v90, v91, 1.0
	v_fmac_f32_e32 v91, v92, v91
	v_div_scale_f32 v92, vcc, 1.0, v89, 1.0
	v_mul_f32_e32 v93, v92, v91
	v_fma_f32 v94, -v90, v93, v92
	v_fmac_f32_e32 v93, v94, v91
	v_fma_f32 v90, -v90, v93, v92
	v_div_fmas_f32 v90, v90, v91, v93
	v_div_fixup_f32 v89, v90, v89, 1.0
	v_div_scale_f32 v90, s[4:5], v88, v88, 1.0
	v_rcp_f32_e32 v91, v90
	s_nop 0
	v_fma_f32 v92, -v90, v91, 1.0
	v_fmac_f32_e32 v91, v92, v91
	v_div_scale_f32 v92, vcc, 1.0, v88, 1.0
	v_mul_f32_e32 v93, v92, v91
	v_fma_f32 v94, -v90, v93, v92
	v_fmac_f32_e32 v93, v94, v91
	v_fma_f32 v90, -v90, v93, v92
	v_div_fmas_f32 v90, v90, v91, v93
	v_div_fixup_f32 v88, v90, v88, 1.0
	v_pk_mul_f32 v[2:3], v[2:3], v[88:89]
	v_mul_f32_e32 v88, 0xbfb8aa3b, v4
	v_mul_f32_e32 v89, 0xbfb8aa3b, v5
	v_exp_f32_e32 v88, v88
	v_exp_f32_e32 v89, v89
	s_nop 0
	v_pk_add_f32 v[88:89], v[88:89], 1.0 op_sel_hi:[1,0]
	s_nop 0
	v_div_scale_f32 v90, s[4:5], v89, v89, 1.0
	v_rcp_f32_e32 v91, v90
	s_nop 0
	v_fma_f32 v92, -v90, v91, 1.0
	v_fmac_f32_e32 v91, v92, v91
	v_div_scale_f32 v92, vcc, 1.0, v89, 1.0
	v_mul_f32_e32 v93, v92, v91
	v_fma_f32 v94, -v90, v93, v92
	v_fmac_f32_e32 v93, v94, v91
	v_fma_f32 v90, -v90, v93, v92
	v_div_fmas_f32 v90, v90, v91, v93
	v_div_fixup_f32 v89, v90, v89, 1.0
	v_div_scale_f32 v90, s[4:5], v88, v88, 1.0
	v_rcp_f32_e32 v91, v90
	s_nop 0
	v_fma_f32 v92, -v90, v91, 1.0
	v_fmac_f32_e32 v91, v92, v91
	v_div_scale_f32 v92, vcc, 1.0, v88, 1.0
	v_mul_f32_e32 v93, v92, v91
	v_fma_f32 v94, -v90, v93, v92
	v_fmac_f32_e32 v93, v94, v91
	v_fma_f32 v90, -v90, v93, v92
	v_div_fmas_f32 v90, v90, v91, v93
	v_div_fixup_f32 v88, v90, v88, 1.0
	v_pk_mul_f32 v[4:5], v[4:5], v[88:89]
	v_mul_f32_e32 v88, 0xbfb8aa3b, v6
	v_mul_f32_e32 v89, 0xbfb8aa3b, v7
	v_exp_f32_e32 v88, v88
	v_exp_f32_e32 v89, v89
	s_nop 0
	v_pk_add_f32 v[88:89], v[88:89], 1.0 op_sel_hi:[1,0]
	s_nop 0
	v_div_scale_f32 v90, s[4:5], v89, v89, 1.0
	v_rcp_f32_e32 v91, v90
	s_nop 0
	v_fma_f32 v92, -v90, v91, 1.0
	v_fmac_f32_e32 v91, v92, v91
	v_div_scale_f32 v92, vcc, 1.0, v89, 1.0
	v_mul_f32_e32 v93, v92, v91
	v_fma_f32 v94, -v90, v93, v92
	v_fmac_f32_e32 v93, v94, v91
	v_fma_f32 v90, -v90, v93, v92
	v_div_fmas_f32 v90, v90, v91, v93
	v_div_fixup_f32 v89, v90, v89, 1.0
	v_div_scale_f32 v90, s[4:5], v88, v88, 1.0
	v_rcp_f32_e32 v91, v90
	s_nop 0
	v_fma_f32 v92, -v90, v91, 1.0
	v_fmac_f32_e32 v91, v92, v91
	v_div_scale_f32 v92, vcc, 1.0, v88, 1.0
	v_mul_f32_e32 v93, v92, v91
	v_fma_f32 v94, -v90, v93, v92
	v_fmac_f32_e32 v93, v94, v91
	v_fma_f32 v90, -v90, v93, v92
	v_div_fmas_f32 v90, v90, v91, v93
	v_div_fixup_f32 v88, v90, v88, 1.0
	v_pk_mul_f32 v[6:7], v[6:7], v[88:89]
	v_mul_f32_e32 v88, 0xbfb8aa3b, v8
	v_mul_f32_e32 v89, 0xbfb8aa3b, v9
	v_exp_f32_e32 v88, v88
	v_exp_f32_e32 v89, v89
	s_nop 0
	v_pk_add_f32 v[88:89], v[88:89], 1.0 op_sel_hi:[1,0]
	s_nop 0
	v_div_scale_f32 v90, s[4:5], v89, v89, 1.0
	v_rcp_f32_e32 v91, v90
	s_nop 0
	v_fma_f32 v92, -v90, v91, 1.0
	v_fmac_f32_e32 v91, v92, v91
	v_div_scale_f32 v92, vcc, 1.0, v89, 1.0
	v_mul_f32_e32 v93, v92, v91
	v_fma_f32 v94, -v90, v93, v92
	v_fmac_f32_e32 v93, v94, v91
	v_fma_f32 v90, -v90, v93, v92
	v_div_fmas_f32 v90, v90, v91, v93
	v_div_fixup_f32 v89, v90, v89, 1.0
	v_div_scale_f32 v90, s[4:5], v88, v88, 1.0
	v_rcp_f32_e32 v91, v90
	s_nop 0
	v_fma_f32 v92, -v90, v91, 1.0
	v_fmac_f32_e32 v91, v92, v91
	v_div_scale_f32 v92, vcc, 1.0, v88, 1.0
	v_mul_f32_e32 v93, v92, v91
	v_fma_f32 v94, -v90, v93, v92
	v_fmac_f32_e32 v93, v94, v91
	v_fma_f32 v90, -v90, v93, v92
	v_div_fmas_f32 v90, v90, v91, v93
	v_div_fixup_f32 v88, v90, v88, 1.0
	v_pk_mul_f32 v[8:9], v[8:9], v[88:89]
	v_mul_f32_e32 v88, 0xbfb8aa3b, v10
	v_mul_f32_e32 v89, 0xbfb8aa3b, v11
	v_exp_f32_e32 v88, v88
	v_exp_f32_e32 v89, v89
	s_nop 0
	v_pk_add_f32 v[88:89], v[88:89], 1.0 op_sel_hi:[1,0]
	s_nop 0
	v_div_scale_f32 v90, s[4:5], v89, v89, 1.0
	v_rcp_f32_e32 v91, v90
	s_nop 0
	v_fma_f32 v92, -v90, v91, 1.0
	v_fmac_f32_e32 v91, v92, v91
	v_div_scale_f32 v92, vcc, 1.0, v89, 1.0
	v_mul_f32_e32 v93, v92, v91
	v_fma_f32 v94, -v90, v93, v92
	v_fmac_f32_e32 v93, v94, v91
	v_fma_f32 v90, -v90, v93, v92
	v_div_fmas_f32 v90, v90, v91, v93
	v_div_fixup_f32 v89, v90, v89, 1.0
	v_div_scale_f32 v90, s[4:5], v88, v88, 1.0
	v_rcp_f32_e32 v91, v90
	s_nop 0
	v_fma_f32 v92, -v90, v91, 1.0
	v_fmac_f32_e32 v91, v92, v91
	v_div_scale_f32 v92, vcc, 1.0, v88, 1.0
	v_mul_f32_e32 v93, v92, v91
	v_fma_f32 v94, -v90, v93, v92
	v_fmac_f32_e32 v93, v94, v91
	v_fma_f32 v90, -v90, v93, v92
	v_div_fmas_f32 v90, v90, v91, v93
	v_div_fixup_f32 v88, v90, v88, 1.0
	v_pk_mul_f32 v[10:11], v[10:11], v[88:89]
	v_mul_f32_e32 v88, 0xbfb8aa3b, v12
	v_mul_f32_e32 v89, 0xbfb8aa3b, v13
	v_exp_f32_e32 v88, v88
	v_exp_f32_e32 v89, v89
	s_nop 0
	v_pk_add_f32 v[88:89], v[88:89], 1.0 op_sel_hi:[1,0]
	s_nop 0
	v_div_scale_f32 v90, s[4:5], v89, v89, 1.0
	v_rcp_f32_e32 v91, v90
	s_nop 0
	v_fma_f32 v92, -v90, v91, 1.0
	v_fmac_f32_e32 v91, v92, v91
	v_div_scale_f32 v92, vcc, 1.0, v89, 1.0
	v_mul_f32_e32 v93, v92, v91
	v_fma_f32 v94, -v90, v93, v92
	v_fmac_f32_e32 v93, v94, v91
	v_fma_f32 v90, -v90, v93, v92
	v_div_fmas_f32 v90, v90, v91, v93
	v_div_fixup_f32 v89, v90, v89, 1.0
	v_div_scale_f32 v90, s[4:5], v88, v88, 1.0
	v_rcp_f32_e32 v91, v90
	s_nop 0
	v_fma_f32 v92, -v90, v91, 1.0
	v_fmac_f32_e32 v91, v92, v91
	v_div_scale_f32 v92, vcc, 1.0, v88, 1.0
	v_mul_f32_e32 v93, v92, v91
	v_fma_f32 v94, -v90, v93, v92
	v_fmac_f32_e32 v93, v94, v91
	v_fma_f32 v90, -v90, v93, v92
	v_div_fmas_f32 v90, v90, v91, v93
	v_div_fixup_f32 v88, v90, v88, 1.0
	v_pk_mul_f32 v[12:13], v[12:13], v[88:89]
	v_mul_f32_e32 v88, 0xbfb8aa3b, v14
	v_mul_f32_e32 v89, 0xbfb8aa3b, v15
	v_exp_f32_e32 v88, v88
	v_exp_f32_e32 v89, v89
	s_nop 0
	v_pk_add_f32 v[88:89], v[88:89], 1.0 op_sel_hi:[1,0]
	s_nop 0
	v_div_scale_f32 v90, s[4:5], v89, v89, 1.0
	v_rcp_f32_e32 v91, v90
	s_nop 0
	v_fma_f32 v92, -v90, v91, 1.0
	v_fmac_f32_e32 v91, v92, v91
	v_div_scale_f32 v92, vcc, 1.0, v89, 1.0
	v_mul_f32_e32 v93, v92, v91
	v_fma_f32 v94, -v90, v93, v92
	v_fmac_f32_e32 v93, v94, v91
	v_fma_f32 v90, -v90, v93, v92
	v_div_fmas_f32 v90, v90, v91, v93
	v_div_fixup_f32 v89, v90, v89, 1.0
	v_div_scale_f32 v90, s[4:5], v88, v88, 1.0
	v_rcp_f32_e32 v91, v90
	s_nop 0
	v_fma_f32 v92, -v90, v91, 1.0
	v_fmac_f32_e32 v91, v92, v91
	v_div_scale_f32 v92, vcc, 1.0, v88, 1.0
	v_mul_f32_e32 v93, v92, v91
	v_fma_f32 v94, -v90, v93, v92
	v_fmac_f32_e32 v93, v94, v91
	v_fma_f32 v90, -v90, v93, v92
	v_div_fmas_f32 v90, v90, v91, v93
	v_div_fixup_f32 v88, v90, v88, 1.0
	v_pk_mul_f32 v[14:15], v[14:15], v[88:89]
	v_mul_f32_e32 v88, 0xbfb8aa3b, v16
	v_mul_f32_e32 v89, 0xbfb8aa3b, v17
	v_exp_f32_e32 v88, v88
	v_exp_f32_e32 v89, v89
	s_nop 0
	v_pk_add_f32 v[88:89], v[88:89], 1.0 op_sel_hi:[1,0]
	s_nop 0
	v_div_scale_f32 v90, s[4:5], v89, v89, 1.0
	v_rcp_f32_e32 v91, v90
	s_nop 0
	v_fma_f32 v92, -v90, v91, 1.0
	v_fmac_f32_e32 v91, v92, v91
	v_div_scale_f32 v92, vcc, 1.0, v89, 1.0
	v_mul_f32_e32 v93, v92, v91
	v_fma_f32 v94, -v90, v93, v92
	v_fmac_f32_e32 v93, v94, v91
	v_fma_f32 v90, -v90, v93, v92
	v_div_fmas_f32 v90, v90, v91, v93
	v_div_fixup_f32 v89, v90, v89, 1.0
	v_div_scale_f32 v90, s[4:5], v88, v88, 1.0
	v_rcp_f32_e32 v91, v90
	s_nop 0
	v_fma_f32 v92, -v90, v91, 1.0
	v_fmac_f32_e32 v91, v92, v91
	v_div_scale_f32 v92, vcc, 1.0, v88, 1.0
	v_mul_f32_e32 v93, v92, v91
	v_fma_f32 v94, -v90, v93, v92
	v_fmac_f32_e32 v93, v94, v91
	v_fma_f32 v90, -v90, v93, v92
	v_div_fmas_f32 v90, v90, v91, v93
	v_div_fixup_f32 v88, v90, v88, 1.0
	v_pk_mul_f32 v[16:17], v[16:17], v[88:89]
	v_mul_f32_e32 v88, 0xbfb8aa3b, v18
	v_mul_f32_e32 v89, 0xbfb8aa3b, v19
	v_exp_f32_e32 v88, v88
	v_exp_f32_e32 v89, v89
	s_nop 0
	v_pk_add_f32 v[88:89], v[88:89], 1.0 op_sel_hi:[1,0]
	s_nop 0
	v_div_scale_f32 v90, s[4:5], v89, v89, 1.0
	v_rcp_f32_e32 v91, v90
	s_nop 0
	v_fma_f32 v92, -v90, v91, 1.0
	v_fmac_f32_e32 v91, v92, v91
	v_div_scale_f32 v92, vcc, 1.0, v89, 1.0
	v_mul_f32_e32 v93, v92, v91
	v_fma_f32 v94, -v90, v93, v92
	v_fmac_f32_e32 v93, v94, v91
	v_fma_f32 v90, -v90, v93, v92
	v_div_fmas_f32 v90, v90, v91, v93
	v_div_fixup_f32 v89, v90, v89, 1.0
	v_div_scale_f32 v90, s[4:5], v88, v88, 1.0
	v_rcp_f32_e32 v91, v90
	s_nop 0
	v_fma_f32 v92, -v90, v91, 1.0
	v_fmac_f32_e32 v91, v92, v91
	v_div_scale_f32 v92, vcc, 1.0, v88, 1.0
	v_mul_f32_e32 v93, v92, v91
	v_fma_f32 v94, -v90, v93, v92
	v_fmac_f32_e32 v93, v94, v91
	v_fma_f32 v90, -v90, v93, v92
	v_div_fmas_f32 v90, v90, v91, v93
	v_div_fixup_f32 v88, v90, v88, 1.0
	v_pk_mul_f32 v[18:19], v[18:19], v[88:89]
	v_mul_f32_e32 v88, 0xbfb8aa3b, v20
	v_mul_f32_e32 v89, 0xbfb8aa3b, v21
	v_exp_f32_e32 v88, v88
	v_exp_f32_e32 v89, v89
	s_nop 0
	v_pk_add_f32 v[88:89], v[88:89], 1.0 op_sel_hi:[1,0]
	s_nop 0
	v_div_scale_f32 v90, s[4:5], v89, v89, 1.0
	v_rcp_f32_e32 v91, v90
	s_nop 0
	v_fma_f32 v92, -v90, v91, 1.0
	v_fmac_f32_e32 v91, v92, v91
	v_div_scale_f32 v92, vcc, 1.0, v89, 1.0
	v_mul_f32_e32 v93, v92, v91
	v_fma_f32 v94, -v90, v93, v92
	v_fmac_f32_e32 v93, v94, v91
	v_fma_f32 v90, -v90, v93, v92
	v_div_fmas_f32 v90, v90, v91, v93
	v_div_fixup_f32 v89, v90, v89, 1.0
	v_div_scale_f32 v90, s[4:5], v88, v88, 1.0
	v_rcp_f32_e32 v91, v90
	s_nop 0
	v_fma_f32 v92, -v90, v91, 1.0
	v_fmac_f32_e32 v91, v92, v91
	v_div_scale_f32 v92, vcc, 1.0, v88, 1.0
	v_mul_f32_e32 v93, v92, v91
	v_fma_f32 v94, -v90, v93, v92
	v_fmac_f32_e32 v93, v94, v91
	v_fma_f32 v90, -v90, v93, v92
	v_div_fmas_f32 v90, v90, v91, v93
	v_div_fixup_f32 v88, v90, v88, 1.0
	v_pk_mul_f32 v[20:21], v[20:21], v[88:89]
	v_mul_f32_e32 v88, 0xbfb8aa3b, v22
	v_mul_f32_e32 v89, 0xbfb8aa3b, v23
	v_exp_f32_e32 v88, v88
	v_exp_f32_e32 v89, v89
	s_nop 0
	v_pk_add_f32 v[88:89], v[88:89], 1.0 op_sel_hi:[1,0]
	s_nop 0
	v_div_scale_f32 v90, s[4:5], v89, v89, 1.0
	v_rcp_f32_e32 v91, v90
	s_nop 0
	v_fma_f32 v92, -v90, v91, 1.0
	v_fmac_f32_e32 v91, v92, v91
	v_div_scale_f32 v92, vcc, 1.0, v89, 1.0
	v_mul_f32_e32 v93, v92, v91
	v_fma_f32 v94, -v90, v93, v92
	v_fmac_f32_e32 v93, v94, v91
	v_fma_f32 v90, -v90, v93, v92
	v_div_fmas_f32 v90, v90, v91, v93
	v_div_fixup_f32 v89, v90, v89, 1.0
	v_div_scale_f32 v90, s[4:5], v88, v88, 1.0
	v_rcp_f32_e32 v91, v90
	s_nop 0
	v_fma_f32 v92, -v90, v91, 1.0
	v_fmac_f32_e32 v91, v92, v91
	v_div_scale_f32 v92, vcc, 1.0, v88, 1.0
	v_mul_f32_e32 v93, v92, v91
	v_fma_f32 v94, -v90, v93, v92
	v_fmac_f32_e32 v93, v94, v91
	v_fma_f32 v90, -v90, v93, v92
	v_div_fmas_f32 v90, v90, v91, v93
	v_div_fixup_f32 v88, v90, v88, 1.0
	v_pk_mul_f32 v[22:23], v[22:23], v[88:89]
	v_mul_f32_e32 v88, 0xbfb8aa3b, v24
	v_mul_f32_e32 v89, 0xbfb8aa3b, v25
	v_exp_f32_e32 v88, v88
	v_exp_f32_e32 v89, v89
	s_nop 0
	v_pk_add_f32 v[88:89], v[88:89], 1.0 op_sel_hi:[1,0]
	s_nop 0
	v_div_scale_f32 v90, s[4:5], v89, v89, 1.0
	v_rcp_f32_e32 v91, v90
	s_nop 0
	v_fma_f32 v92, -v90, v91, 1.0
	v_fmac_f32_e32 v91, v92, v91
	v_div_scale_f32 v92, vcc, 1.0, v89, 1.0
	v_mul_f32_e32 v93, v92, v91
	v_fma_f32 v94, -v90, v93, v92
	v_fmac_f32_e32 v93, v94, v91
	v_fma_f32 v90, -v90, v93, v92
	v_div_fmas_f32 v90, v90, v91, v93
	v_div_fixup_f32 v89, v90, v89, 1.0
	v_div_scale_f32 v90, s[4:5], v88, v88, 1.0
	v_rcp_f32_e32 v91, v90
	s_nop 0
	v_fma_f32 v92, -v90, v91, 1.0
	v_fmac_f32_e32 v91, v92, v91
	v_div_scale_f32 v92, vcc, 1.0, v88, 1.0
	v_mul_f32_e32 v93, v92, v91
	v_fma_f32 v94, -v90, v93, v92
	v_fmac_f32_e32 v93, v94, v91
	v_fma_f32 v90, -v90, v93, v92
	v_div_fmas_f32 v90, v90, v91, v93
	v_div_fixup_f32 v88, v90, v88, 1.0
	v_pk_mul_f32 v[24:25], v[24:25], v[88:89]
	v_mul_f32_e32 v88, 0xbfb8aa3b, v26
	v_mul_f32_e32 v89, 0xbfb8aa3b, v27
	v_exp_f32_e32 v88, v88
	v_exp_f32_e32 v89, v89
	s_nop 0
	v_pk_add_f32 v[88:89], v[88:89], 1.0 op_sel_hi:[1,0]
	s_nop 0
	v_div_scale_f32 v90, s[4:5], v89, v89, 1.0
	v_rcp_f32_e32 v91, v90
	s_nop 0
	v_fma_f32 v92, -v90, v91, 1.0
	v_fmac_f32_e32 v91, v92, v91
	v_div_scale_f32 v92, vcc, 1.0, v89, 1.0
	v_mul_f32_e32 v93, v92, v91
	v_fma_f32 v94, -v90, v93, v92
	v_fmac_f32_e32 v93, v94, v91
	v_fma_f32 v90, -v90, v93, v92
	v_div_fmas_f32 v90, v90, v91, v93
	v_div_fixup_f32 v89, v90, v89, 1.0
	v_div_scale_f32 v90, s[4:5], v88, v88, 1.0
	v_rcp_f32_e32 v91, v90
	s_nop 0
	v_fma_f32 v92, -v90, v91, 1.0
	v_fmac_f32_e32 v91, v92, v91
	v_div_scale_f32 v92, vcc, 1.0, v88, 1.0
	v_mul_f32_e32 v93, v92, v91
	v_fma_f32 v94, -v90, v93, v92
	v_fmac_f32_e32 v93, v94, v91
	v_fma_f32 v90, -v90, v93, v92
	v_div_fmas_f32 v90, v90, v91, v93
	v_div_fixup_f32 v88, v90, v88, 1.0
	v_pk_mul_f32 v[26:27], v[26:27], v[88:89]
	v_mul_f32_e32 v88, 0xbfb8aa3b, v28
	v_mul_f32_e32 v89, 0xbfb8aa3b, v29
	v_exp_f32_e32 v88, v88
	v_exp_f32_e32 v89, v89
	s_nop 0
	v_pk_add_f32 v[88:89], v[88:89], 1.0 op_sel_hi:[1,0]
	s_nop 0
	v_div_scale_f32 v90, s[4:5], v89, v89, 1.0
	v_rcp_f32_e32 v91, v90
	s_nop 0
	v_fma_f32 v92, -v90, v91, 1.0
	v_fmac_f32_e32 v91, v92, v91
	v_div_scale_f32 v92, vcc, 1.0, v89, 1.0
	v_mul_f32_e32 v93, v92, v91
	v_fma_f32 v94, -v90, v93, v92
	v_fmac_f32_e32 v93, v94, v91
	v_fma_f32 v90, -v90, v93, v92
	v_div_fmas_f32 v90, v90, v91, v93
	v_div_fixup_f32 v89, v90, v89, 1.0
	v_div_scale_f32 v90, s[4:5], v88, v88, 1.0
	v_rcp_f32_e32 v91, v90
	s_nop 0
	v_fma_f32 v92, -v90, v91, 1.0
	v_fmac_f32_e32 v91, v92, v91
	v_div_scale_f32 v92, vcc, 1.0, v88, 1.0
	v_mul_f32_e32 v93, v92, v91
	v_fma_f32 v94, -v90, v93, v92
	v_fmac_f32_e32 v93, v94, v91
	v_fma_f32 v90, -v90, v93, v92
	v_div_fmas_f32 v90, v90, v91, v93
	v_div_fixup_f32 v88, v90, v88, 1.0
	v_pk_mul_f32 v[28:29], v[28:29], v[88:89]
	v_mul_f32_e32 v88, 0xbfb8aa3b, v30
	v_mul_f32_e32 v89, 0xbfb8aa3b, v31
	v_exp_f32_e32 v88, v88
	v_exp_f32_e32 v89, v89
	s_nop 0
	v_pk_add_f32 v[88:89], v[88:89], 1.0 op_sel_hi:[1,0]
	s_nop 0
	v_div_scale_f32 v90, s[4:5], v89, v89, 1.0
	v_rcp_f32_e32 v91, v90
	s_nop 0
	v_fma_f32 v92, -v90, v91, 1.0
	v_fmac_f32_e32 v91, v92, v91
	v_div_scale_f32 v92, vcc, 1.0, v89, 1.0
	v_mul_f32_e32 v93, v92, v91
	v_fma_f32 v94, -v90, v93, v92
	v_fmac_f32_e32 v93, v94, v91
	v_fma_f32 v90, -v90, v93, v92
	v_div_fmas_f32 v90, v90, v91, v93
	v_div_fixup_f32 v89, v90, v89, 1.0
	v_div_scale_f32 v90, s[4:5], v88, v88, 1.0
	v_rcp_f32_e32 v91, v90
	s_nop 0
	v_fma_f32 v92, -v90, v91, 1.0
	v_fmac_f32_e32 v91, v92, v91
	v_div_scale_f32 v92, vcc, 1.0, v88, 1.0
	v_mul_f32_e32 v93, v92, v91
	v_fma_f32 v94, -v90, v93, v92
	v_fmac_f32_e32 v93, v94, v91
	v_fma_f32 v90, -v90, v93, v92
	v_div_fmas_f32 v90, v90, v91, v93
	v_div_fixup_f32 v88, v90, v88, 1.0
	v_pk_mul_f32 v[30:31], v[30:31], v[88:89]
.Lcv_nosilu:
	global_store_dwordx4 v220, v[0:3], s[72:73]
	s_add_u32 s72, s72, s39
	s_addc_u32 s73, s73, 0
	global_store_dwordx4 v220, v[4:7], s[72:73]
	s_add_u32 s72, s72, s39
	s_addc_u32 s73, s73, 0
	global_store_dwordx4 v220, v[8:11], s[72:73]
	s_add_u32 s72, s72, s39
	s_addc_u32 s73, s73, 0
	global_store_dwordx4 v220, v[12:15], s[72:73]
	s_add_u32 s72, s72, s39
	s_addc_u32 s73, s73, 0
	global_store_dwordx4 v220, v[16:19], s[72:73]
	s_add_u32 s72, s72, s39
	s_addc_u32 s73, s73, 0
	global_store_dwordx4 v220, v[20:23], s[72:73]
	s_add_u32 s72, s72, s39
	s_addc_u32 s73, s73, 0
	global_store_dwordx4 v220, v[24:27], s[72:73]
	s_add_u32 s72, s72, s39
	s_addc_u32 s73, s73, 0
	global_store_dwordx4 v220, v[28:31], s[72:73]
	s_add_u32 s72, s72, s39
	s_addc_u32 s73, s73, 0
	s_add_u32 s16, s16, 1
	s_cmp_lt_u32 s16, 2
	s_cbranch_scc1 .Lcv_half
	s_branch .LBB0_312
